# phase 0 mod GEMM: silu(c) operand staging unrolled with ~34 loads in flight (was one load + vmcnt(0) per element, 80 serial round trips per job)
# speedup vs baseline: 1.0499x; 1.0237x over previous
.LBB0_61:
	v_lshlrev_b32_e32 v44, 2, v0
	v_mad_u32_u24 v45, v150, s9, v95
	global_load_dword v10, v44, s[80:81]
	v_add_u32_e32 v44, 0x2000, v44
	global_load_dword v11, v44, s[80:81]
	v_add_u32_e32 v44, 0x2000, v44
	global_load_dword v12, v44, s[80:81]
	v_add_u32_e32 v44, 0x2000, v44
	global_load_dword v13, v44, s[80:81]
	v_add_u32_e32 v44, 0x2000, v44
	v_subrev_u32_e32 v44, 0x8000, v44
	global_load_dword v14, v44, s[82:83]
	v_add_u32_e32 v44, 0x2000, v44
	global_load_dword v15, v44, s[82:83]
	v_add_u32_e32 v44, 0x2000, v44
	global_load_dword v16, v44, s[82:83]
	v_add_u32_e32 v44, 0x2000, v44
	global_load_dword v17, v44, s[82:83]
	v_add_u32_e32 v44, 0x2000, v44
	global_load_dword v18, v44, s[82:83]
	v_add_u32_e32 v44, 0x2000, v44
	global_load_dword v19, v44, s[82:83]
	v_add_u32_e32 v44, 0x2000, v44
	global_load_dword v20, v44, s[82:83]
	v_add_u32_e32 v44, 0x2000, v44
	global_load_dword v21, v44, s[82:83]
	v_add_u32_e32 v44, 0x2000, v44
	global_load_dword v22, v44, s[82:83]
	v_add_u32_e32 v44, 0x2000, v44
	global_load_dword v23, v44, s[82:83]
	v_add_u32_e32 v44, 0x2000, v44
	global_load_dword v24, v44, s[82:83]
	v_add_u32_e32 v44, 0x2000, v44
	global_load_dword v25, v44, s[82:83]
	v_add_u32_e32 v44, 0x2000, v44
	global_load_dword v26, v44, s[82:83]
	v_add_u32_e32 v44, 0x2000, v44
	global_load_dword v27, v44, s[82:83]
	v_add_u32_e32 v44, 0x2000, v44
	global_load_dword v28, v44, s[82:83]
	v_add_u32_e32 v44, 0x2000, v44
	global_load_dword v29, v44, s[82:83]
	v_add_u32_e32 v44, 0x2000, v44
	global_load_dword v30, v44, s[82:83]
	v_add_u32_e32 v44, 0x2000, v44
	global_load_dword v31, v44, s[82:83]
	v_add_u32_e32 v44, 0x2000, v44
	global_load_dword v32, v44, s[82:83]
	v_add_u32_e32 v44, 0x2000, v44
	global_load_dword v33, v44, s[82:83]
	v_add_u32_e32 v44, 0x2000, v44
	global_load_dword v34, v44, s[82:83]
	v_add_u32_e32 v44, 0x2000, v44
	global_load_dword v35, v44, s[82:83]
	v_add_u32_e32 v44, 0x2000, v44
	global_load_dword v36, v44, s[82:83]
	v_add_u32_e32 v44, 0x2000, v44
	global_load_dword v37, v44, s[82:83]
	v_add_u32_e32 v44, 0x2000, v44
	global_load_dword v38, v44, s[82:83]
	v_add_u32_e32 v44, 0x2000, v44
	global_load_dword v39, v44, s[82:83]
	v_add_u32_e32 v44, 0x2000, v44
	global_load_dword v40, v44, s[82:83]
	v_add_u32_e32 v44, 0x2000, v44
	global_load_dword v41, v44, s[82:83]
	v_add_u32_e32 v44, 0x2000, v44
	global_load_dword v42, v44, s[82:83]
	v_add_u32_e32 v44, 0x2000, v44
	global_load_dword v43, v44, s[82:83]
	v_add_u32_e32 v44, 0x2000, v44
	s_waitcnt vmcnt(33)
	v_mul_f32_e32 v4, 0xbfb8aa3b, v10
	v_exp_f32_e32 v4, v4
	s_nop 0
	v_add_f32_e32 v4, 1.0, v4
	v_div_scale_f32 v5, s[36:37], v4, v4, v10
	v_rcp_f32_e32 v6, v5
	v_div_scale_f32 v7, vcc, v10, v4, v10
	v_fma_f32 v8, -v5, v6, 1.0
	v_fmac_f32_e32 v6, v8, v6
	v_mul_f32_e32 v8, v7, v6
	v_fma_f32 v9, -v5, v8, v7
	v_fmac_f32_e32 v8, v9, v6
	v_fma_f32 v5, -v5, v8, v7
	v_div_fmas_f32 v5, v5, v6, v8
	v_div_fixup_f32 v3, v5, v4, v10
	v_bfe_u32 v4, v3, 16, 1
	v_add3_u32 v3, v3, v4, s12
	ds_write_b16_d16_hi v45, v3
	global_load_dword v10, v44, s[82:83]
	v_add_u32_e32 v44, 0x2000, v44
	s_waitcnt vmcnt(33)
	v_mul_f32_e32 v4, 0xbfb8aa3b, v11
	v_exp_f32_e32 v4, v4
	s_nop 0
	v_add_f32_e32 v4, 1.0, v4
	v_div_scale_f32 v5, s[36:37], v4, v4, v11
	v_rcp_f32_e32 v6, v5
	v_div_scale_f32 v7, vcc, v11, v4, v11
	v_fma_f32 v8, -v5, v6, 1.0
	v_fmac_f32_e32 v6, v8, v6
	v_mul_f32_e32 v8, v7, v6
	v_fma_f32 v9, -v5, v8, v7
	v_fmac_f32_e32 v8, v9, v6
	v_fma_f32 v5, -v5, v8, v7
	v_div_fmas_f32 v5, v5, v6, v8
	v_div_fixup_f32 v3, v5, v4, v11
	v_bfe_u32 v4, v3, 16, 1
	v_add3_u32 v3, v3, v4, s12
	ds_write_b16_d16_hi v45, v3 offset:544
	global_load_dword v11, v44, s[82:83]
	v_add_u32_e32 v44, 0x2000, v44
	s_waitcnt vmcnt(33)
	v_mul_f32_e32 v4, 0xbfb8aa3b, v12
	v_exp_f32_e32 v4, v4
	s_nop 0
	v_add_f32_e32 v4, 1.0, v4
	v_div_scale_f32 v5, s[36:37], v4, v4, v12
	v_rcp_f32_e32 v6, v5
	v_div_scale_f32 v7, vcc, v12, v4, v12
	v_fma_f32 v8, -v5, v6, 1.0
	v_fmac_f32_e32 v6, v8, v6
	v_mul_f32_e32 v8, v7, v6
	v_fma_f32 v9, -v5, v8, v7
	v_fmac_f32_e32 v8, v9, v6
	v_fma_f32 v5, -v5, v8, v7
	v_div_fmas_f32 v5, v5, v6, v8
	v_div_fixup_f32 v3, v5, v4, v12
	v_bfe_u32 v4, v3, 16, 1
	v_add3_u32 v3, v3, v4, s12
	ds_write_b16_d16_hi v45, v3 offset:1088
	global_load_dword v12, v44, s[82:83]
	v_add_u32_e32 v44, 0x2000, v44
	s_waitcnt vmcnt(33)
	v_mul_f32_e32 v4, 0xbfb8aa3b, v13
	v_exp_f32_e32 v4, v4
	s_nop 0
	v_add_f32_e32 v4, 1.0, v4
	v_div_scale_f32 v5, s[36:37], v4, v4, v13
	v_rcp_f32_e32 v6, v5
	v_div_scale_f32 v7, vcc, v13, v4, v13
	v_fma_f32 v8, -v5, v6, 1.0
	v_fmac_f32_e32 v6, v8, v6
	v_mul_f32_e32 v8, v7, v6
	v_fma_f32 v9, -v5, v8, v7
	v_fmac_f32_e32 v8, v9, v6
	v_fma_f32 v5, -v5, v8, v7
	v_div_fmas_f32 v5, v5, v6, v8
	v_div_fixup_f32 v3, v5, v4, v13
	v_bfe_u32 v4, v3, 16, 1
	v_add3_u32 v3, v3, v4, s12
	ds_write_b16_d16_hi v45, v3 offset:1632
	global_load_dword v13, v44, s[82:83]
	v_add_u32_e32 v44, 0x2000, v44
	s_waitcnt vmcnt(33)
	v_mul_f32_e32 v4, 0xbfb8aa3b, v14
	v_exp_f32_e32 v4, v4
	s_nop 0
	v_add_f32_e32 v4, 1.0, v4
	v_div_scale_f32 v5, s[36:37], v4, v4, v14
	v_rcp_f32_e32 v6, v5
	v_div_scale_f32 v7, vcc, v14, v4, v14
	v_fma_f32 v8, -v5, v6, 1.0
	v_fmac_f32_e32 v6, v8, v6
	v_mul_f32_e32 v8, v7, v6
	v_fma_f32 v9, -v5, v8, v7
	v_fmac_f32_e32 v8, v9, v6
	v_fma_f32 v5, -v5, v8, v7
	v_div_fmas_f32 v5, v5, v6, v8
	v_div_fixup_f32 v3, v5, v4, v14
	v_bfe_u32 v4, v3, 16, 1
	v_add3_u32 v3, v3, v4, s12
	ds_write_b16_d16_hi v45, v3 offset:2176
	global_load_dword v14, v44, s[82:83]
	v_add_u32_e32 v44, 0x2000, v44
	s_waitcnt vmcnt(33)
	v_mul_f32_e32 v4, 0xbfb8aa3b, v15
	v_exp_f32_e32 v4, v4
	s_nop 0
	v_add_f32_e32 v4, 1.0, v4
	v_div_scale_f32 v5, s[36:37], v4, v4, v15
	v_rcp_f32_e32 v6, v5
	v_div_scale_f32 v7, vcc, v15, v4, v15
	v_fma_f32 v8, -v5, v6, 1.0
	v_fmac_f32_e32 v6, v8, v6
	v_mul_f32_e32 v8, v7, v6
	v_fma_f32 v9, -v5, v8, v7
	v_fmac_f32_e32 v8, v9, v6
	v_fma_f32 v5, -v5, v8, v7
	v_div_fmas_f32 v5, v5, v6, v8
	v_div_fixup_f32 v3, v5, v4, v15
	v_bfe_u32 v4, v3, 16, 1
	v_add3_u32 v3, v3, v4, s12
	ds_write_b16_d16_hi v45, v3 offset:2720
	global_load_dword v15, v44, s[82:83]
	v_add_u32_e32 v44, 0x2000, v44
	s_waitcnt vmcnt(33)
	v_mul_f32_e32 v4, 0xbfb8aa3b, v16
	v_exp_f32_e32 v4, v4
	s_nop 0
	v_add_f32_e32 v4, 1.0, v4
	v_div_scale_f32 v5, s[36:37], v4, v4, v16
	v_rcp_f32_e32 v6, v5
	v_div_scale_f32 v7, vcc, v16, v4, v16
	v_fma_f32 v8, -v5, v6, 1.0
	v_fmac_f32_e32 v6, v8, v6
	v_mul_f32_e32 v8, v7, v6
	v_fma_f32 v9, -v5, v8, v7
	v_fmac_f32_e32 v8, v9, v6
	v_fma_f32 v5, -v5, v8, v7
	v_div_fmas_f32 v5, v5, v6, v8
	v_div_fixup_f32 v3, v5, v4, v16
	v_bfe_u32 v4, v3, 16, 1
	v_add3_u32 v3, v3, v4, s12
	ds_write_b16_d16_hi v45, v3 offset:3264
	global_load_dword v16, v44, s[82:83]
	v_add_u32_e32 v44, 0x2000, v44
	s_waitcnt vmcnt(33)
	v_mul_f32_e32 v4, 0xbfb8aa3b, v17
	v_exp_f32_e32 v4, v4
	s_nop 0
	v_add_f32_e32 v4, 1.0, v4
	v_div_scale_f32 v5, s[36:37], v4, v4, v17
	v_rcp_f32_e32 v6, v5
	v_div_scale_f32 v7, vcc, v17, v4, v17
	v_fma_f32 v8, -v5, v6, 1.0
	v_fmac_f32_e32 v6, v8, v6
	v_mul_f32_e32 v8, v7, v6
	v_fma_f32 v9, -v5, v8, v7
	v_fmac_f32_e32 v8, v9, v6
	v_fma_f32 v5, -v5, v8, v7
	v_div_fmas_f32 v5, v5, v6, v8
	v_div_fixup_f32 v3, v5, v4, v17
	v_bfe_u32 v4, v3, 16, 1
	v_add3_u32 v3, v3, v4, s12
	ds_write_b16_d16_hi v45, v3 offset:3808
	global_load_dword v17, v44, s[82:83]
	v_add_u32_e32 v44, 0x2000, v44
	s_waitcnt vmcnt(33)
	v_mul_f32_e32 v4, 0xbfb8aa3b, v18
	v_exp_f32_e32 v4, v4
	s_nop 0
	v_add_f32_e32 v4, 1.0, v4
	v_div_scale_f32 v5, s[36:37], v4, v4, v18
	v_rcp_f32_e32 v6, v5
	v_div_scale_f32 v7, vcc, v18, v4, v18
	v_fma_f32 v8, -v5, v6, 1.0
	v_fmac_f32_e32 v6, v8, v6
	v_mul_f32_e32 v8, v7, v6
	v_fma_f32 v9, -v5, v8, v7
	v_fmac_f32_e32 v8, v9, v6
	v_fma_f32 v5, -v5, v8, v7
	v_div_fmas_f32 v5, v5, v6, v8
	v_div_fixup_f32 v3, v5, v4, v18
	v_bfe_u32 v4, v3, 16, 1
	v_add3_u32 v3, v3, v4, s12
	ds_write_b16_d16_hi v45, v3 offset:4352
	global_load_dword v18, v44, s[82:83]
	v_add_u32_e32 v44, 0x2000, v44
	s_waitcnt vmcnt(33)
	v_mul_f32_e32 v4, 0xbfb8aa3b, v19
	v_exp_f32_e32 v4, v4
	s_nop 0
	v_add_f32_e32 v4, 1.0, v4
	v_div_scale_f32 v5, s[36:37], v4, v4, v19
	v_rcp_f32_e32 v6, v5
	v_div_scale_f32 v7, vcc, v19, v4, v19
	v_fma_f32 v8, -v5, v6, 1.0
	v_fmac_f32_e32 v6, v8, v6
	v_mul_f32_e32 v8, v7, v6
	v_fma_f32 v9, -v5, v8, v7
	v_fmac_f32_e32 v8, v9, v6
	v_fma_f32 v5, -v5, v8, v7
	v_div_fmas_f32 v5, v5, v6, v8
	v_div_fixup_f32 v3, v5, v4, v19
	v_bfe_u32 v4, v3, 16, 1
	v_add3_u32 v3, v3, v4, s12
	ds_write_b16_d16_hi v45, v3 offset:4896
	global_load_dword v19, v44, s[82:83]
	v_add_u32_e32 v44, 0x2000, v44
	s_waitcnt vmcnt(33)
	v_mul_f32_e32 v4, 0xbfb8aa3b, v20
	v_exp_f32_e32 v4, v4
	s_nop 0
	v_add_f32_e32 v4, 1.0, v4
	v_div_scale_f32 v5, s[36:37], v4, v4, v20
	v_rcp_f32_e32 v6, v5
	v_div_scale_f32 v7, vcc, v20, v4, v20
	v_fma_f32 v8, -v5, v6, 1.0
	v_fmac_f32_e32 v6, v8, v6
	v_mul_f32_e32 v8, v7, v6
	v_fma_f32 v9, -v5, v8, v7
	v_fmac_f32_e32 v8, v9, v6
	v_fma_f32 v5, -v5, v8, v7
	v_div_fmas_f32 v5, v5, v6, v8
	v_div_fixup_f32 v3, v5, v4, v20
	v_bfe_u32 v4, v3, 16, 1
	v_add3_u32 v3, v3, v4, s12
	ds_write_b16_d16_hi v45, v3 offset:5440
	global_load_dword v20, v44, s[82:83]
	v_add_u32_e32 v44, 0x2000, v44
	s_waitcnt vmcnt(33)
	v_mul_f32_e32 v4, 0xbfb8aa3b, v21
	v_exp_f32_e32 v4, v4
	s_nop 0
	v_add_f32_e32 v4, 1.0, v4
	v_div_scale_f32 v5, s[36:37], v4, v4, v21
	v_rcp_f32_e32 v6, v5
	v_div_scale_f32 v7, vcc, v21, v4, v21
	v_fma_f32 v8, -v5, v6, 1.0
	v_fmac_f32_e32 v6, v8, v6
	v_mul_f32_e32 v8, v7, v6
	v_fma_f32 v9, -v5, v8, v7
	v_fmac_f32_e32 v8, v9, v6
	v_fma_f32 v5, -v5, v8, v7
	v_div_fmas_f32 v5, v5, v6, v8
	v_div_fixup_f32 v3, v5, v4, v21
	v_bfe_u32 v4, v3, 16, 1
	v_add3_u32 v3, v3, v4, s12
	ds_write_b16_d16_hi v45, v3 offset:5984
	global_load_dword v21, v44, s[82:83]
	v_add_u32_e32 v44, 0x2000, v44
	s_waitcnt vmcnt(33)
	v_mul_f32_e32 v4, 0xbfb8aa3b, v22
	v_exp_f32_e32 v4, v4
	s_nop 0
	v_add_f32_e32 v4, 1.0, v4
	v_div_scale_f32 v5, s[36:37], v4, v4, v22
	v_rcp_f32_e32 v6, v5
	v_div_scale_f32 v7, vcc, v22, v4, v22
	v_fma_f32 v8, -v5, v6, 1.0
	v_fmac_f32_e32 v6, v8, v6
	v_mul_f32_e32 v8, v7, v6
	v_fma_f32 v9, -v5, v8, v7
	v_fmac_f32_e32 v8, v9, v6
	v_fma_f32 v5, -v5, v8, v7
	v_div_fmas_f32 v5, v5, v6, v8
	v_div_fixup_f32 v3, v5, v4, v22
	v_bfe_u32 v4, v3, 16, 1
	v_add3_u32 v3, v3, v4, s12
	ds_write_b16_d16_hi v45, v3 offset:6528
	global_load_dword v22, v44, s[82:83]
	v_add_u32_e32 v44, 0x2000, v44
	s_waitcnt vmcnt(33)
	v_mul_f32_e32 v4, 0xbfb8aa3b, v23
	v_exp_f32_e32 v4, v4
	s_nop 0
	v_add_f32_e32 v4, 1.0, v4
	v_div_scale_f32 v5, s[36:37], v4, v4, v23
	v_rcp_f32_e32 v6, v5
	v_div_scale_f32 v7, vcc, v23, v4, v23
	v_fma_f32 v8, -v5, v6, 1.0
	v_fmac_f32_e32 v6, v8, v6
	v_mul_f32_e32 v8, v7, v6
	v_fma_f32 v9, -v5, v8, v7
	v_fmac_f32_e32 v8, v9, v6
	v_fma_f32 v5, -v5, v8, v7
	v_div_fmas_f32 v5, v5, v6, v8
	v_div_fixup_f32 v3, v5, v4, v23
	v_bfe_u32 v4, v3, 16, 1
	v_add3_u32 v3, v3, v4, s12
	ds_write_b16_d16_hi v45, v3 offset:7072
	global_load_dword v23, v44, s[82:83]
	v_add_u32_e32 v44, 0x2000, v44
	s_waitcnt vmcnt(33)
	v_mul_f32_e32 v4, 0xbfb8aa3b, v24
	v_exp_f32_e32 v4, v4
	s_nop 0
	v_add_f32_e32 v4, 1.0, v4
	v_div_scale_f32 v5, s[36:37], v4, v4, v24
	v_rcp_f32_e32 v6, v5
	v_div_scale_f32 v7, vcc, v24, v4, v24
	v_fma_f32 v8, -v5, v6, 1.0
	v_fmac_f32_e32 v6, v8, v6
	v_mul_f32_e32 v8, v7, v6
	v_fma_f32 v9, -v5, v8, v7
	v_fmac_f32_e32 v8, v9, v6
	v_fma_f32 v5, -v5, v8, v7
	v_div_fmas_f32 v5, v5, v6, v8
	v_div_fixup_f32 v3, v5, v4, v24
	v_bfe_u32 v4, v3, 16, 1
	v_add3_u32 v3, v3, v4, s12
	ds_write_b16_d16_hi v45, v3 offset:7616
	global_load_dword v24, v44, s[82:83]
	v_add_u32_e32 v44, 0x2000, v44
	s_waitcnt vmcnt(33)
	v_mul_f32_e32 v4, 0xbfb8aa3b, v25
	v_exp_f32_e32 v4, v4
	s_nop 0
	v_add_f32_e32 v4, 1.0, v4
	v_div_scale_f32 v5, s[36:37], v4, v4, v25
	v_rcp_f32_e32 v6, v5
	v_div_scale_f32 v7, vcc, v25, v4, v25
	v_fma_f32 v8, -v5, v6, 1.0
	v_fmac_f32_e32 v6, v8, v6
	v_mul_f32_e32 v8, v7, v6
	v_fma_f32 v9, -v5, v8, v7
	v_fmac_f32_e32 v8, v9, v6
	v_fma_f32 v5, -v5, v8, v7
	v_div_fmas_f32 v5, v5, v6, v8
	v_div_fixup_f32 v3, v5, v4, v25
	v_bfe_u32 v4, v3, 16, 1
	v_add3_u32 v3, v3, v4, s12
	ds_write_b16_d16_hi v45, v3 offset:8160
	global_load_dword v25, v44, s[82:83]
	v_add_u32_e32 v44, 0x2000, v44
	s_waitcnt vmcnt(33)
	v_mul_f32_e32 v4, 0xbfb8aa3b, v26
	v_exp_f32_e32 v4, v4
	s_nop 0
	v_add_f32_e32 v4, 1.0, v4
	v_div_scale_f32 v5, s[36:37], v4, v4, v26
	v_rcp_f32_e32 v6, v5
	v_div_scale_f32 v7, vcc, v26, v4, v26
	v_fma_f32 v8, -v5, v6, 1.0
	v_fmac_f32_e32 v6, v8, v6
	v_mul_f32_e32 v8, v7, v6
	v_fma_f32 v9, -v5, v8, v7
	v_fmac_f32_e32 v8, v9, v6
	v_fma_f32 v5, -v5, v8, v7
	v_div_fmas_f32 v5, v5, v6, v8
	v_div_fixup_f32 v3, v5, v4, v26
	v_bfe_u32 v4, v3, 16, 1
	v_add3_u32 v3, v3, v4, s12
	ds_write_b16_d16_hi v45, v3 offset:8704
	global_load_dword v26, v44, s[82:83]
	v_add_u32_e32 v44, 0x2000, v44
	s_waitcnt vmcnt(33)
	v_mul_f32_e32 v4, 0xbfb8aa3b, v27
	v_exp_f32_e32 v4, v4
	s_nop 0
	v_add_f32_e32 v4, 1.0, v4
	v_div_scale_f32 v5, s[36:37], v4, v4, v27
	v_rcp_f32_e32 v6, v5
	v_div_scale_f32 v7, vcc, v27, v4, v27
	v_fma_f32 v8, -v5, v6, 1.0
	v_fmac_f32_e32 v6, v8, v6
	v_mul_f32_e32 v8, v7, v6
	v_fma_f32 v9, -v5, v8, v7
	v_fmac_f32_e32 v8, v9, v6
	v_fma_f32 v5, -v5, v8, v7
	v_div_fmas_f32 v5, v5, v6, v8
	v_div_fixup_f32 v3, v5, v4, v27
	v_bfe_u32 v4, v3, 16, 1
	v_add3_u32 v3, v3, v4, s12
	ds_write_b16_d16_hi v45, v3 offset:9248
	global_load_dword v27, v44, s[82:83]
	v_add_u32_e32 v44, 0x2000, v44
	s_waitcnt vmcnt(33)
	v_mul_f32_e32 v4, 0xbfb8aa3b, v28
	v_exp_f32_e32 v4, v4
	s_nop 0
	v_add_f32_e32 v4, 1.0, v4
	v_div_scale_f32 v5, s[36:37], v4, v4, v28
	v_rcp_f32_e32 v6, v5
	v_div_scale_f32 v7, vcc, v28, v4, v28
	v_fma_f32 v8, -v5, v6, 1.0
	v_fmac_f32_e32 v6, v8, v6
	v_mul_f32_e32 v8, v7, v6
	v_fma_f32 v9, -v5, v8, v7
	v_fmac_f32_e32 v8, v9, v6
	v_fma_f32 v5, -v5, v8, v7
	v_div_fmas_f32 v5, v5, v6, v8
	v_div_fixup_f32 v3, v5, v4, v28
	v_bfe_u32 v4, v3, 16, 1
	v_add3_u32 v3, v3, v4, s12
	ds_write_b16_d16_hi v45, v3 offset:9792
	global_load_dword v28, v44, s[82:83]
	v_add_u32_e32 v44, 0x2000, v44
	s_waitcnt vmcnt(33)
	v_mul_f32_e32 v4, 0xbfb8aa3b, v29
	v_exp_f32_e32 v4, v4
	s_nop 0
	v_add_f32_e32 v4, 1.0, v4
	v_div_scale_f32 v5, s[36:37], v4, v4, v29
	v_rcp_f32_e32 v6, v5
	v_div_scale_f32 v7, vcc, v29, v4, v29
	v_fma_f32 v8, -v5, v6, 1.0
	v_fmac_f32_e32 v6, v8, v6
	v_mul_f32_e32 v8, v7, v6
	v_fma_f32 v9, -v5, v8, v7
	v_fmac_f32_e32 v8, v9, v6
	v_fma_f32 v5, -v5, v8, v7
	v_div_fmas_f32 v5, v5, v6, v8
	v_div_fixup_f32 v3, v5, v4, v29
	v_bfe_u32 v4, v3, 16, 1
	v_add3_u32 v3, v3, v4, s12
	ds_write_b16_d16_hi v45, v3 offset:10336
	global_load_dword v29, v44, s[82:83]
	v_add_u32_e32 v44, 0x2000, v44
	s_waitcnt vmcnt(33)
	v_mul_f32_e32 v4, 0xbfb8aa3b, v30
	v_exp_f32_e32 v4, v4
	s_nop 0
	v_add_f32_e32 v4, 1.0, v4
	v_div_scale_f32 v5, s[36:37], v4, v4, v30
	v_rcp_f32_e32 v6, v5
	v_div_scale_f32 v7, vcc, v30, v4, v30
	v_fma_f32 v8, -v5, v6, 1.0
	v_fmac_f32_e32 v6, v8, v6
	v_mul_f32_e32 v8, v7, v6
	v_fma_f32 v9, -v5, v8, v7
	v_fmac_f32_e32 v8, v9, v6
	v_fma_f32 v5, -v5, v8, v7
	v_div_fmas_f32 v5, v5, v6, v8
	v_div_fixup_f32 v3, v5, v4, v30
	v_bfe_u32 v4, v3, 16, 1
	v_add3_u32 v3, v3, v4, s12
	ds_write_b16_d16_hi v45, v3 offset:10880
	global_load_dword v30, v44, s[82:83]
	v_add_u32_e32 v44, 0x2000, v44
	s_waitcnt vmcnt(33)
	v_mul_f32_e32 v4, 0xbfb8aa3b, v31
	v_exp_f32_e32 v4, v4
	s_nop 0
	v_add_f32_e32 v4, 1.0, v4
	v_div_scale_f32 v5, s[36:37], v4, v4, v31
	v_rcp_f32_e32 v6, v5
	v_div_scale_f32 v7, vcc, v31, v4, v31
	v_fma_f32 v8, -v5, v6, 1.0
	v_fmac_f32_e32 v6, v8, v6
	v_mul_f32_e32 v8, v7, v6
	v_fma_f32 v9, -v5, v8, v7
	v_fmac_f32_e32 v8, v9, v6
	v_fma_f32 v5, -v5, v8, v7
	v_div_fmas_f32 v5, v5, v6, v8
	v_div_fixup_f32 v3, v5, v4, v31
	v_bfe_u32 v4, v3, 16, 1
	v_add3_u32 v3, v3, v4, s12
	ds_write_b16_d16_hi v45, v3 offset:11424
	global_load_dword v31, v44, s[82:83]
	v_add_u32_e32 v44, 0x2000, v44
	s_waitcnt vmcnt(33)
	v_mul_f32_e32 v4, 0xbfb8aa3b, v32
	v_exp_f32_e32 v4, v4
	s_nop 0
	v_add_f32_e32 v4, 1.0, v4
	v_div_scale_f32 v5, s[36:37], v4, v4, v32
	v_rcp_f32_e32 v6, v5
	v_div_scale_f32 v7, vcc, v32, v4, v32
	v_fma_f32 v8, -v5, v6, 1.0
	v_fmac_f32_e32 v6, v8, v6
	v_mul_f32_e32 v8, v7, v6
	v_fma_f32 v9, -v5, v8, v7
	v_fmac_f32_e32 v8, v9, v6
	v_fma_f32 v5, -v5, v8, v7
	v_div_fmas_f32 v5, v5, v6, v8
	v_div_fixup_f32 v3, v5, v4, v32
	v_bfe_u32 v4, v3, 16, 1
	v_add3_u32 v3, v3, v4, s12
	ds_write_b16_d16_hi v45, v3 offset:11968
	global_load_dword v32, v44, s[82:83]
	v_add_u32_e32 v44, 0x2000, v44
	s_waitcnt vmcnt(33)
	v_mul_f32_e32 v4, 0xbfb8aa3b, v33
	v_exp_f32_e32 v4, v4
	s_nop 0
	v_add_f32_e32 v4, 1.0, v4
	v_div_scale_f32 v5, s[36:37], v4, v4, v33
	v_rcp_f32_e32 v6, v5
	v_div_scale_f32 v7, vcc, v33, v4, v33
	v_fma_f32 v8, -v5, v6, 1.0
	v_fmac_f32_e32 v6, v8, v6
	v_mul_f32_e32 v8, v7, v6
	v_fma_f32 v9, -v5, v8, v7
	v_fmac_f32_e32 v8, v9, v6
	v_fma_f32 v5, -v5, v8, v7
	v_div_fmas_f32 v5, v5, v6, v8
	v_div_fixup_f32 v3, v5, v4, v33
	v_bfe_u32 v4, v3, 16, 1
	v_add3_u32 v3, v3, v4, s12
	ds_write_b16_d16_hi v45, v3 offset:12512
	global_load_dword v33, v44, s[82:83]
	v_add_u32_e32 v44, 0x2000, v44
	s_waitcnt vmcnt(33)
	v_mul_f32_e32 v4, 0xbfb8aa3b, v34
	v_exp_f32_e32 v4, v4
	s_nop 0
	v_add_f32_e32 v4, 1.0, v4
	v_div_scale_f32 v5, s[36:37], v4, v4, v34
	v_rcp_f32_e32 v6, v5
	v_div_scale_f32 v7, vcc, v34, v4, v34
	v_fma_f32 v8, -v5, v6, 1.0
	v_fmac_f32_e32 v6, v8, v6
	v_mul_f32_e32 v8, v7, v6
	v_fma_f32 v9, -v5, v8, v7
	v_fmac_f32_e32 v8, v9, v6
	v_fma_f32 v5, -v5, v8, v7
	v_div_fmas_f32 v5, v5, v6, v8
	v_div_fixup_f32 v3, v5, v4, v34
	v_bfe_u32 v4, v3, 16, 1
	v_add3_u32 v3, v3, v4, s12
	ds_write_b16_d16_hi v45, v3 offset:13056
	global_load_dword v34, v44, s[82:83]
	v_add_u32_e32 v44, 0x2000, v44
	s_waitcnt vmcnt(33)
	v_mul_f32_e32 v4, 0xbfb8aa3b, v35
	v_exp_f32_e32 v4, v4
	s_nop 0
	v_add_f32_e32 v4, 1.0, v4
	v_div_scale_f32 v5, s[36:37], v4, v4, v35
	v_rcp_f32_e32 v6, v5
	v_div_scale_f32 v7, vcc, v35, v4, v35
	v_fma_f32 v8, -v5, v6, 1.0
	v_fmac_f32_e32 v6, v8, v6
	v_mul_f32_e32 v8, v7, v6
	v_fma_f32 v9, -v5, v8, v7
	v_fmac_f32_e32 v8, v9, v6
	v_fma_f32 v5, -v5, v8, v7
	v_div_fmas_f32 v5, v5, v6, v8
	v_div_fixup_f32 v3, v5, v4, v35
	v_bfe_u32 v4, v3, 16, 1
	v_add3_u32 v3, v3, v4, s12
	ds_write_b16_d16_hi v45, v3 offset:13600
	global_load_dword v35, v44, s[82:83]
	v_add_u32_e32 v44, 0x2000, v44
	s_waitcnt vmcnt(33)
	v_mul_f32_e32 v4, 0xbfb8aa3b, v36
	v_exp_f32_e32 v4, v4
	s_nop 0
	v_add_f32_e32 v4, 1.0, v4
	v_div_scale_f32 v5, s[36:37], v4, v4, v36
	v_rcp_f32_e32 v6, v5
	v_div_scale_f32 v7, vcc, v36, v4, v36
	v_fma_f32 v8, -v5, v6, 1.0
	v_fmac_f32_e32 v6, v8, v6
	v_mul_f32_e32 v8, v7, v6
	v_fma_f32 v9, -v5, v8, v7
	v_fmac_f32_e32 v8, v9, v6
	v_fma_f32 v5, -v5, v8, v7
	v_div_fmas_f32 v5, v5, v6, v8
	v_div_fixup_f32 v3, v5, v4, v36
	v_bfe_u32 v4, v3, 16, 1
	v_add3_u32 v3, v3, v4, s12
	ds_write_b16_d16_hi v45, v3 offset:14144
	global_load_dword v36, v44, s[82:83]
	v_add_u32_e32 v44, 0x2000, v44
	s_waitcnt vmcnt(33)
	v_mul_f32_e32 v4, 0xbfb8aa3b, v37
	v_exp_f32_e32 v4, v4
	s_nop 0
	v_add_f32_e32 v4, 1.0, v4
	v_div_scale_f32 v5, s[36:37], v4, v4, v37
	v_rcp_f32_e32 v6, v5
	v_div_scale_f32 v7, vcc, v37, v4, v37
	v_fma_f32 v8, -v5, v6, 1.0
	v_fmac_f32_e32 v6, v8, v6
	v_mul_f32_e32 v8, v7, v6
	v_fma_f32 v9, -v5, v8, v7
	v_fmac_f32_e32 v8, v9, v6
	v_fma_f32 v5, -v5, v8, v7
	v_div_fmas_f32 v5, v5, v6, v8
	v_div_fixup_f32 v3, v5, v4, v37
	v_bfe_u32 v4, v3, 16, 1
	v_add3_u32 v3, v3, v4, s12
	ds_write_b16_d16_hi v45, v3 offset:14688
	global_load_dword v37, v44, s[82:83]
	v_add_u32_e32 v44, 0x2000, v44
	s_waitcnt vmcnt(33)
	v_mul_f32_e32 v4, 0xbfb8aa3b, v38
	v_exp_f32_e32 v4, v4
	s_nop 0
	v_add_f32_e32 v4, 1.0, v4
	v_div_scale_f32 v5, s[36:37], v4, v4, v38
	v_rcp_f32_e32 v6, v5
	v_div_scale_f32 v7, vcc, v38, v4, v38
	v_fma_f32 v8, -v5, v6, 1.0
	v_fmac_f32_e32 v6, v8, v6
	v_mul_f32_e32 v8, v7, v6
	v_fma_f32 v9, -v5, v8, v7
	v_fmac_f32_e32 v8, v9, v6
	v_fma_f32 v5, -v5, v8, v7
	v_div_fmas_f32 v5, v5, v6, v8
	v_div_fixup_f32 v3, v5, v4, v38
	v_bfe_u32 v4, v3, 16, 1
	v_add3_u32 v3, v3, v4, s12
	ds_write_b16_d16_hi v45, v3 offset:15232
	global_load_dword v38, v44, s[82:83]
	v_add_u32_e32 v44, 0x2000, v44
	s_waitcnt vmcnt(33)
	v_mul_f32_e32 v4, 0xbfb8aa3b, v39
	v_exp_f32_e32 v4, v4
	s_nop 0
	v_add_f32_e32 v4, 1.0, v4
	v_div_scale_f32 v5, s[36:37], v4, v4, v39
	v_rcp_f32_e32 v6, v5
	v_div_scale_f32 v7, vcc, v39, v4, v39
	v_fma_f32 v8, -v5, v6, 1.0
	v_fmac_f32_e32 v6, v8, v6
	v_mul_f32_e32 v8, v7, v6
	v_fma_f32 v9, -v5, v8, v7
	v_fmac_f32_e32 v8, v9, v6
	v_fma_f32 v5, -v5, v8, v7
	v_div_fmas_f32 v5, v5, v6, v8
	v_div_fixup_f32 v3, v5, v4, v39
	v_bfe_u32 v4, v3, 16, 1
	v_add3_u32 v3, v3, v4, s12
	ds_write_b16_d16_hi v45, v3 offset:15776
	global_load_dword v39, v44, s[82:83]
	v_add_u32_e32 v44, 0x2000, v44
	s_waitcnt vmcnt(33)
	v_mul_f32_e32 v4, 0xbfb8aa3b, v40
	v_exp_f32_e32 v4, v4
	s_nop 0
	v_add_f32_e32 v4, 1.0, v4
	v_div_scale_f32 v5, s[36:37], v4, v4, v40
	v_rcp_f32_e32 v6, v5
	v_div_scale_f32 v7, vcc, v40, v4, v40
	v_fma_f32 v8, -v5, v6, 1.0
	v_fmac_f32_e32 v6, v8, v6
	v_mul_f32_e32 v8, v7, v6
	v_fma_f32 v9, -v5, v8, v7
	v_fmac_f32_e32 v8, v9, v6
	v_fma_f32 v5, -v5, v8, v7
	v_div_fmas_f32 v5, v5, v6, v8
	v_div_fixup_f32 v3, v5, v4, v40
	v_bfe_u32 v4, v3, 16, 1
	v_add3_u32 v3, v3, v4, s12
	ds_write_b16_d16_hi v45, v3 offset:16320
	global_load_dword v40, v44, s[82:83]
	v_add_u32_e32 v44, 0x2000, v44
	s_waitcnt vmcnt(33)
	v_mul_f32_e32 v4, 0xbfb8aa3b, v41
	v_exp_f32_e32 v4, v4
	s_nop 0
	v_add_f32_e32 v4, 1.0, v4
	v_div_scale_f32 v5, s[36:37], v4, v4, v41
	v_rcp_f32_e32 v6, v5
	v_div_scale_f32 v7, vcc, v41, v4, v41
	v_fma_f32 v8, -v5, v6, 1.0
	v_fmac_f32_e32 v6, v8, v6
	v_mul_f32_e32 v8, v7, v6
	v_fma_f32 v9, -v5, v8, v7
	v_fmac_f32_e32 v8, v9, v6
	v_fma_f32 v5, -v5, v8, v7
	v_div_fmas_f32 v5, v5, v6, v8
	v_div_fixup_f32 v3, v5, v4, v41
	v_bfe_u32 v4, v3, 16, 1
	v_add3_u32 v3, v3, v4, s12
	ds_write_b16_d16_hi v45, v3 offset:16864
	global_load_dword v41, v44, s[82:83]
	v_add_u32_e32 v44, 0x2000, v44
	s_waitcnt vmcnt(33)
	v_mul_f32_e32 v4, 0xbfb8aa3b, v42
	v_exp_f32_e32 v4, v4
	s_nop 0
	v_add_f32_e32 v4, 1.0, v4
	v_div_scale_f32 v5, s[36:37], v4, v4, v42
	v_rcp_f32_e32 v6, v5
	v_div_scale_f32 v7, vcc, v42, v4, v42
	v_fma_f32 v8, -v5, v6, 1.0
	v_fmac_f32_e32 v6, v8, v6
	v_mul_f32_e32 v8, v7, v6
	v_fma_f32 v9, -v5, v8, v7
	v_fmac_f32_e32 v8, v9, v6
	v_fma_f32 v5, -v5, v8, v7
	v_div_fmas_f32 v5, v5, v6, v8
	v_div_fixup_f32 v3, v5, v4, v42
	v_bfe_u32 v4, v3, 16, 1
	v_add3_u32 v3, v3, v4, s12
	ds_write_b16_d16_hi v45, v3 offset:17408
	global_load_dword v42, v44, s[82:83]
	v_add_u32_e32 v44, 0x2000, v44
	s_waitcnt vmcnt(33)
	v_mul_f32_e32 v4, 0xbfb8aa3b, v43
	v_exp_f32_e32 v4, v4
	s_nop 0
	v_add_f32_e32 v4, 1.0, v4
	v_div_scale_f32 v5, s[36:37], v4, v4, v43
	v_rcp_f32_e32 v6, v5
	v_div_scale_f32 v7, vcc, v43, v4, v43
	v_fma_f32 v8, -v5, v6, 1.0
	v_fmac_f32_e32 v6, v8, v6
	v_mul_f32_e32 v8, v7, v6
	v_fma_f32 v9, -v5, v8, v7
	v_fmac_f32_e32 v8, v9, v6
	v_fma_f32 v5, -v5, v8, v7
	v_div_fmas_f32 v5, v5, v6, v8
	v_div_fixup_f32 v3, v5, v4, v43
	v_bfe_u32 v4, v3, 16, 1
	v_add3_u32 v3, v3, v4, s12
	ds_write_b16_d16_hi v45, v3 offset:17952
	global_load_dword v43, v44, s[82:83]
	v_add_u32_e32 v44, 0x2000, v44
	s_waitcnt vmcnt(33)
	v_mul_f32_e32 v4, 0xbfb8aa3b, v10
	v_exp_f32_e32 v4, v4
	s_nop 0
	v_add_f32_e32 v4, 1.0, v4
	v_div_scale_f32 v5, s[36:37], v4, v4, v10
	v_rcp_f32_e32 v6, v5
	v_div_scale_f32 v7, vcc, v10, v4, v10
	v_fma_f32 v8, -v5, v6, 1.0
	v_fmac_f32_e32 v6, v8, v6
	v_mul_f32_e32 v8, v7, v6
	v_fma_f32 v9, -v5, v8, v7
	v_fmac_f32_e32 v8, v9, v6
	v_fma_f32 v5, -v5, v8, v7
	v_div_fmas_f32 v5, v5, v6, v8
	v_div_fixup_f32 v3, v5, v4, v10
	v_bfe_u32 v4, v3, 16, 1
	v_add3_u32 v3, v3, v4, s12
	ds_write_b16_d16_hi v45, v3 offset:18496
	s_waitcnt vmcnt(32)
	v_mul_f32_e32 v4, 0xbfb8aa3b, v11
	v_exp_f32_e32 v4, v4
	s_nop 0
	v_add_f32_e32 v4, 1.0, v4
	v_div_scale_f32 v5, s[36:37], v4, v4, v11
	v_rcp_f32_e32 v6, v5
	v_div_scale_f32 v7, vcc, v11, v4, v11
	v_fma_f32 v8, -v5, v6, 1.0
	v_fmac_f32_e32 v6, v8, v6
	v_mul_f32_e32 v8, v7, v6
	v_fma_f32 v9, -v5, v8, v7
	v_fmac_f32_e32 v8, v9, v6
	v_fma_f32 v5, -v5, v8, v7
	v_div_fmas_f32 v5, v5, v6, v8
	v_div_fixup_f32 v3, v5, v4, v11
	v_bfe_u32 v4, v3, 16, 1
	v_add3_u32 v3, v3, v4, s12
	ds_write_b16_d16_hi v45, v3 offset:19040
	s_waitcnt vmcnt(31)
	v_mul_f32_e32 v4, 0xbfb8aa3b, v12
	v_exp_f32_e32 v4, v4
	s_nop 0
	v_add_f32_e32 v4, 1.0, v4
	v_div_scale_f32 v5, s[36:37], v4, v4, v12
	v_rcp_f32_e32 v6, v5
	v_div_scale_f32 v7, vcc, v12, v4, v12
	v_fma_f32 v8, -v5, v6, 1.0
	v_fmac_f32_e32 v6, v8, v6
	v_mul_f32_e32 v8, v7, v6
	v_fma_f32 v9, -v5, v8, v7
	v_fmac_f32_e32 v8, v9, v6
	v_fma_f32 v5, -v5, v8, v7
	v_div_fmas_f32 v5, v5, v6, v8
	v_div_fixup_f32 v3, v5, v4, v12
	v_bfe_u32 v4, v3, 16, 1
	v_add3_u32 v3, v3, v4, s12
	ds_write_b16_d16_hi v45, v3 offset:19584
	s_waitcnt vmcnt(30)
	v_mul_f32_e32 v4, 0xbfb8aa3b, v13
	v_exp_f32_e32 v4, v4
	s_nop 0
	v_add_f32_e32 v4, 1.0, v4
	v_div_scale_f32 v5, s[36:37], v4, v4, v13
	v_rcp_f32_e32 v6, v5
	v_div_scale_f32 v7, vcc, v13, v4, v13
	v_fma_f32 v8, -v5, v6, 1.0
	v_fmac_f32_e32 v6, v8, v6
	v_mul_f32_e32 v8, v7, v6
	v_fma_f32 v9, -v5, v8, v7
	v_fmac_f32_e32 v8, v9, v6
	v_fma_f32 v5, -v5, v8, v7
	v_div_fmas_f32 v5, v5, v6, v8
	v_div_fixup_f32 v3, v5, v4, v13
	v_bfe_u32 v4, v3, 16, 1
	v_add3_u32 v3, v3, v4, s12
	ds_write_b16_d16_hi v45, v3 offset:20128
	s_waitcnt vmcnt(29)
	v_mul_f32_e32 v4, 0xbfb8aa3b, v14
	v_exp_f32_e32 v4, v4
	s_nop 0
	v_add_f32_e32 v4, 1.0, v4
	v_div_scale_f32 v5, s[36:37], v4, v4, v14
	v_rcp_f32_e32 v6, v5
	v_div_scale_f32 v7, vcc, v14, v4, v14
	v_fma_f32 v8, -v5, v6, 1.0
	v_fmac_f32_e32 v6, v8, v6
	v_mul_f32_e32 v8, v7, v6
	v_fma_f32 v9, -v5, v8, v7
	v_fmac_f32_e32 v8, v9, v6
	v_fma_f32 v5, -v5, v8, v7
	v_div_fmas_f32 v5, v5, v6, v8
	v_div_fixup_f32 v3, v5, v4, v14
	v_bfe_u32 v4, v3, 16, 1
	v_add3_u32 v3, v3, v4, s12
	ds_write_b16_d16_hi v45, v3 offset:20672
	s_waitcnt vmcnt(28)
	v_mul_f32_e32 v4, 0xbfb8aa3b, v15
	v_exp_f32_e32 v4, v4
	s_nop 0
	v_add_f32_e32 v4, 1.0, v4
	v_div_scale_f32 v5, s[36:37], v4, v4, v15
	v_rcp_f32_e32 v6, v5
	v_div_scale_f32 v7, vcc, v15, v4, v15
	v_fma_f32 v8, -v5, v6, 1.0
	v_fmac_f32_e32 v6, v8, v6
	v_mul_f32_e32 v8, v7, v6
	v_fma_f32 v9, -v5, v8, v7
	v_fmac_f32_e32 v8, v9, v6
	v_fma_f32 v5, -v5, v8, v7
	v_div_fmas_f32 v5, v5, v6, v8
	v_div_fixup_f32 v3, v5, v4, v15
	v_bfe_u32 v4, v3, 16, 1
	v_add3_u32 v3, v3, v4, s12
	ds_write_b16_d16_hi v45, v3 offset:21216
	s_waitcnt vmcnt(27)
	v_mul_f32_e32 v4, 0xbfb8aa3b, v16
	v_exp_f32_e32 v4, v4
	s_nop 0
	v_add_f32_e32 v4, 1.0, v4
	v_div_scale_f32 v5, s[36:37], v4, v4, v16
	v_rcp_f32_e32 v6, v5
	v_div_scale_f32 v7, vcc, v16, v4, v16
	v_fma_f32 v8, -v5, v6, 1.0
	v_fmac_f32_e32 v6, v8, v6
	v_mul_f32_e32 v8, v7, v6
	v_fma_f32 v9, -v5, v8, v7
	v_fmac_f32_e32 v8, v9, v6
	v_fma_f32 v5, -v5, v8, v7
	v_div_fmas_f32 v5, v5, v6, v8
	v_div_fixup_f32 v3, v5, v4, v16
	v_bfe_u32 v4, v3, 16, 1
	v_add3_u32 v3, v3, v4, s12
	ds_write_b16_d16_hi v45, v3 offset:21760
	s_waitcnt vmcnt(26)
	v_mul_f32_e32 v4, 0xbfb8aa3b, v17
	v_exp_f32_e32 v4, v4
	s_nop 0
	v_add_f32_e32 v4, 1.0, v4
	v_div_scale_f32 v5, s[36:37], v4, v4, v17
	v_rcp_f32_e32 v6, v5
	v_div_scale_f32 v7, vcc, v17, v4, v17
	v_fma_f32 v8, -v5, v6, 1.0
	v_fmac_f32_e32 v6, v8, v6
	v_mul_f32_e32 v8, v7, v6
	v_fma_f32 v9, -v5, v8, v7
	v_fmac_f32_e32 v8, v9, v6
	v_fma_f32 v5, -v5, v8, v7
	v_div_fmas_f32 v5, v5, v6, v8
	v_div_fixup_f32 v3, v5, v4, v17
	v_bfe_u32 v4, v3, 16, 1
	v_add3_u32 v3, v3, v4, s12
	ds_write_b16_d16_hi v45, v3 offset:22304
	s_waitcnt vmcnt(25)
	v_mul_f32_e32 v4, 0xbfb8aa3b, v18
	v_exp_f32_e32 v4, v4
	s_nop 0
	v_add_f32_e32 v4, 1.0, v4
	v_div_scale_f32 v5, s[36:37], v4, v4, v18
	v_rcp_f32_e32 v6, v5
	v_div_scale_f32 v7, vcc, v18, v4, v18
	v_fma_f32 v8, -v5, v6, 1.0
	v_fmac_f32_e32 v6, v8, v6
	v_mul_f32_e32 v8, v7, v6
	v_fma_f32 v9, -v5, v8, v7
	v_fmac_f32_e32 v8, v9, v6
	v_fma_f32 v5, -v5, v8, v7
	v_div_fmas_f32 v5, v5, v6, v8
	v_div_fixup_f32 v3, v5, v4, v18
	v_bfe_u32 v4, v3, 16, 1
	v_add3_u32 v3, v3, v4, s12
	ds_write_b16_d16_hi v45, v3 offset:22848
	s_waitcnt vmcnt(24)
	v_mul_f32_e32 v4, 0xbfb8aa3b, v19
	v_exp_f32_e32 v4, v4
	s_nop 0
	v_add_f32_e32 v4, 1.0, v4
	v_div_scale_f32 v5, s[36:37], v4, v4, v19
	v_rcp_f32_e32 v6, v5
	v_div_scale_f32 v7, vcc, v19, v4, v19
	v_fma_f32 v8, -v5, v6, 1.0
	v_fmac_f32_e32 v6, v8, v6
	v_mul_f32_e32 v8, v7, v6
	v_fma_f32 v9, -v5, v8, v7
	v_fmac_f32_e32 v8, v9, v6
	v_fma_f32 v5, -v5, v8, v7
	v_div_fmas_f32 v5, v5, v6, v8
	v_div_fixup_f32 v3, v5, v4, v19
	v_bfe_u32 v4, v3, 16, 1
	v_add3_u32 v3, v3, v4, s12
	ds_write_b16_d16_hi v45, v3 offset:23392
	s_waitcnt vmcnt(23)
	v_mul_f32_e32 v4, 0xbfb8aa3b, v20
	v_exp_f32_e32 v4, v4
	s_nop 0
	v_add_f32_e32 v4, 1.0, v4
	v_div_scale_f32 v5, s[36:37], v4, v4, v20
	v_rcp_f32_e32 v6, v5
	v_div_scale_f32 v7, vcc, v20, v4, v20
	v_fma_f32 v8, -v5, v6, 1.0
	v_fmac_f32_e32 v6, v8, v6
	v_mul_f32_e32 v8, v7, v6
	v_fma_f32 v9, -v5, v8, v7
	v_fmac_f32_e32 v8, v9, v6
	v_fma_f32 v5, -v5, v8, v7
	v_div_fmas_f32 v5, v5, v6, v8
	v_div_fixup_f32 v3, v5, v4, v20
	v_bfe_u32 v4, v3, 16, 1
	v_add3_u32 v3, v3, v4, s12
	ds_write_b16_d16_hi v45, v3 offset:23936
	s_waitcnt vmcnt(22)
	v_mul_f32_e32 v4, 0xbfb8aa3b, v21
	v_exp_f32_e32 v4, v4
	s_nop 0
	v_add_f32_e32 v4, 1.0, v4
	v_div_scale_f32 v5, s[36:37], v4, v4, v21
	v_rcp_f32_e32 v6, v5
	v_div_scale_f32 v7, vcc, v21, v4, v21
	v_fma_f32 v8, -v5, v6, 1.0
	v_fmac_f32_e32 v6, v8, v6
	v_mul_f32_e32 v8, v7, v6
	v_fma_f32 v9, -v5, v8, v7
	v_fmac_f32_e32 v8, v9, v6
	v_fma_f32 v5, -v5, v8, v7
	v_div_fmas_f32 v5, v5, v6, v8
	v_div_fixup_f32 v3, v5, v4, v21
	v_bfe_u32 v4, v3, 16, 1
	v_add3_u32 v3, v3, v4, s12
	ds_write_b16_d16_hi v45, v3 offset:24480
	s_waitcnt vmcnt(21)
	v_mul_f32_e32 v4, 0xbfb8aa3b, v22
	v_exp_f32_e32 v4, v4
	s_nop 0
	v_add_f32_e32 v4, 1.0, v4
	v_div_scale_f32 v5, s[36:37], v4, v4, v22
	v_rcp_f32_e32 v6, v5
	v_div_scale_f32 v7, vcc, v22, v4, v22
	v_fma_f32 v8, -v5, v6, 1.0
	v_fmac_f32_e32 v6, v8, v6
	v_mul_f32_e32 v8, v7, v6
	v_fma_f32 v9, -v5, v8, v7
	v_fmac_f32_e32 v8, v9, v6
	v_fma_f32 v5, -v5, v8, v7
	v_div_fmas_f32 v5, v5, v6, v8
	v_div_fixup_f32 v3, v5, v4, v22
	v_bfe_u32 v4, v3, 16, 1
	v_add3_u32 v3, v3, v4, s12
	ds_write_b16_d16_hi v45, v3 offset:25024
	s_waitcnt vmcnt(20)
	v_mul_f32_e32 v4, 0xbfb8aa3b, v23
	v_exp_f32_e32 v4, v4
	s_nop 0
	v_add_f32_e32 v4, 1.0, v4
	v_div_scale_f32 v5, s[36:37], v4, v4, v23
	v_rcp_f32_e32 v6, v5
	v_div_scale_f32 v7, vcc, v23, v4, v23
	v_fma_f32 v8, -v5, v6, 1.0
	v_fmac_f32_e32 v6, v8, v6
	v_mul_f32_e32 v8, v7, v6
	v_fma_f32 v9, -v5, v8, v7
	v_fmac_f32_e32 v8, v9, v6
	v_fma_f32 v5, -v5, v8, v7
	v_div_fmas_f32 v5, v5, v6, v8
	v_div_fixup_f32 v3, v5, v4, v23
	v_bfe_u32 v4, v3, 16, 1
	v_add3_u32 v3, v3, v4, s12
	ds_write_b16_d16_hi v45, v3 offset:25568
	s_waitcnt vmcnt(19)
	v_mul_f32_e32 v4, 0xbfb8aa3b, v24
	v_exp_f32_e32 v4, v4
	s_nop 0
	v_add_f32_e32 v4, 1.0, v4
	v_div_scale_f32 v5, s[36:37], v4, v4, v24
	v_rcp_f32_e32 v6, v5
	v_div_scale_f32 v7, vcc, v24, v4, v24
	v_fma_f32 v8, -v5, v6, 1.0
	v_fmac_f32_e32 v6, v8, v6
	v_mul_f32_e32 v8, v7, v6
	v_fma_f32 v9, -v5, v8, v7
	v_fmac_f32_e32 v8, v9, v6
	v_fma_f32 v5, -v5, v8, v7
	v_div_fmas_f32 v5, v5, v6, v8
	v_div_fixup_f32 v3, v5, v4, v24
	v_bfe_u32 v4, v3, 16, 1
	v_add3_u32 v3, v3, v4, s12
	ds_write_b16_d16_hi v45, v3 offset:26112
	s_waitcnt vmcnt(18)
	v_mul_f32_e32 v4, 0xbfb8aa3b, v25
	v_exp_f32_e32 v4, v4
	s_nop 0
	v_add_f32_e32 v4, 1.0, v4
	v_div_scale_f32 v5, s[36:37], v4, v4, v25
	v_rcp_f32_e32 v6, v5
	v_div_scale_f32 v7, vcc, v25, v4, v25
	v_fma_f32 v8, -v5, v6, 1.0
	v_fmac_f32_e32 v6, v8, v6
	v_mul_f32_e32 v8, v7, v6
	v_fma_f32 v9, -v5, v8, v7
	v_fmac_f32_e32 v8, v9, v6
	v_fma_f32 v5, -v5, v8, v7
	v_div_fmas_f32 v5, v5, v6, v8
	v_div_fixup_f32 v3, v5, v4, v25
	v_bfe_u32 v4, v3, 16, 1
	v_add3_u32 v3, v3, v4, s12
	ds_write_b16_d16_hi v45, v3 offset:26656
	s_waitcnt vmcnt(17)
	v_mul_f32_e32 v4, 0xbfb8aa3b, v26
	v_exp_f32_e32 v4, v4
	s_nop 0
	v_add_f32_e32 v4, 1.0, v4
	v_div_scale_f32 v5, s[36:37], v4, v4, v26
	v_rcp_f32_e32 v6, v5
	v_div_scale_f32 v7, vcc, v26, v4, v26
	v_fma_f32 v8, -v5, v6, 1.0
	v_fmac_f32_e32 v6, v8, v6
	v_mul_f32_e32 v8, v7, v6
	v_fma_f32 v9, -v5, v8, v7
	v_fmac_f32_e32 v8, v9, v6
	v_fma_f32 v5, -v5, v8, v7
	v_div_fmas_f32 v5, v5, v6, v8
	v_div_fixup_f32 v3, v5, v4, v26
	v_bfe_u32 v4, v3, 16, 1
	v_add3_u32 v3, v3, v4, s12
	ds_write_b16_d16_hi v45, v3 offset:27200
	s_waitcnt vmcnt(16)
	v_mul_f32_e32 v4, 0xbfb8aa3b, v27
	v_exp_f32_e32 v4, v4
	s_nop 0
	v_add_f32_e32 v4, 1.0, v4
	v_div_scale_f32 v5, s[36:37], v4, v4, v27
	v_rcp_f32_e32 v6, v5
	v_div_scale_f32 v7, vcc, v27, v4, v27
	v_fma_f32 v8, -v5, v6, 1.0
	v_fmac_f32_e32 v6, v8, v6
	v_mul_f32_e32 v8, v7, v6
	v_fma_f32 v9, -v5, v8, v7
	v_fmac_f32_e32 v8, v9, v6
	v_fma_f32 v5, -v5, v8, v7
	v_div_fmas_f32 v5, v5, v6, v8
	v_div_fixup_f32 v3, v5, v4, v27
	v_bfe_u32 v4, v3, 16, 1
	v_add3_u32 v3, v3, v4, s12
	ds_write_b16_d16_hi v45, v3 offset:27744
	s_waitcnt vmcnt(15)
	v_mul_f32_e32 v4, 0xbfb8aa3b, v28
	v_exp_f32_e32 v4, v4
	s_nop 0
	v_add_f32_e32 v4, 1.0, v4
	v_div_scale_f32 v5, s[36:37], v4, v4, v28
	v_rcp_f32_e32 v6, v5
	v_div_scale_f32 v7, vcc, v28, v4, v28
	v_fma_f32 v8, -v5, v6, 1.0
	v_fmac_f32_e32 v6, v8, v6
	v_mul_f32_e32 v8, v7, v6
	v_fma_f32 v9, -v5, v8, v7
	v_fmac_f32_e32 v8, v9, v6
	v_fma_f32 v5, -v5, v8, v7
	v_div_fmas_f32 v5, v5, v6, v8
	v_div_fixup_f32 v3, v5, v4, v28
	v_bfe_u32 v4, v3, 16, 1
	v_add3_u32 v3, v3, v4, s12
	ds_write_b16_d16_hi v45, v3 offset:28288
	s_waitcnt vmcnt(14)
	v_mul_f32_e32 v4, 0xbfb8aa3b, v29
	v_exp_f32_e32 v4, v4
	s_nop 0
	v_add_f32_e32 v4, 1.0, v4
	v_div_scale_f32 v5, s[36:37], v4, v4, v29
	v_rcp_f32_e32 v6, v5
	v_div_scale_f32 v7, vcc, v29, v4, v29
	v_fma_f32 v8, -v5, v6, 1.0
	v_fmac_f32_e32 v6, v8, v6
	v_mul_f32_e32 v8, v7, v6
	v_fma_f32 v9, -v5, v8, v7
	v_fmac_f32_e32 v8, v9, v6
	v_fma_f32 v5, -v5, v8, v7
	v_div_fmas_f32 v5, v5, v6, v8
	v_div_fixup_f32 v3, v5, v4, v29
	v_bfe_u32 v4, v3, 16, 1
	v_add3_u32 v3, v3, v4, s12
	ds_write_b16_d16_hi v45, v3 offset:28832
	s_waitcnt vmcnt(13)
	v_mul_f32_e32 v4, 0xbfb8aa3b, v30
	v_exp_f32_e32 v4, v4
	s_nop 0
	v_add_f32_e32 v4, 1.0, v4
	v_div_scale_f32 v5, s[36:37], v4, v4, v30
	v_rcp_f32_e32 v6, v5
	v_div_scale_f32 v7, vcc, v30, v4, v30
	v_fma_f32 v8, -v5, v6, 1.0
	v_fmac_f32_e32 v6, v8, v6
	v_mul_f32_e32 v8, v7, v6
	v_fma_f32 v9, -v5, v8, v7
	v_fmac_f32_e32 v8, v9, v6
	v_fma_f32 v5, -v5, v8, v7
	v_div_fmas_f32 v5, v5, v6, v8
	v_div_fixup_f32 v3, v5, v4, v30
	v_bfe_u32 v4, v3, 16, 1
	v_add3_u32 v3, v3, v4, s12
	ds_write_b16_d16_hi v45, v3 offset:29376
	s_waitcnt vmcnt(12)
	v_mul_f32_e32 v4, 0xbfb8aa3b, v31
	v_exp_f32_e32 v4, v4
	s_nop 0
	v_add_f32_e32 v4, 1.0, v4
	v_div_scale_f32 v5, s[36:37], v4, v4, v31
	v_rcp_f32_e32 v6, v5
	v_div_scale_f32 v7, vcc, v31, v4, v31
	v_fma_f32 v8, -v5, v6, 1.0
	v_fmac_f32_e32 v6, v8, v6
	v_mul_f32_e32 v8, v7, v6
	v_fma_f32 v9, -v5, v8, v7
	v_fmac_f32_e32 v8, v9, v6
	v_fma_f32 v5, -v5, v8, v7
	v_div_fmas_f32 v5, v5, v6, v8
	v_div_fixup_f32 v3, v5, v4, v31
	v_bfe_u32 v4, v3, 16, 1
	v_add3_u32 v3, v3, v4, s12
	ds_write_b16_d16_hi v45, v3 offset:29920
	s_waitcnt vmcnt(11)
	v_mul_f32_e32 v4, 0xbfb8aa3b, v32
	v_exp_f32_e32 v4, v4
	s_nop 0
	v_add_f32_e32 v4, 1.0, v4
	v_div_scale_f32 v5, s[36:37], v4, v4, v32
	v_rcp_f32_e32 v6, v5
	v_div_scale_f32 v7, vcc, v32, v4, v32
	v_fma_f32 v8, -v5, v6, 1.0
	v_fmac_f32_e32 v6, v8, v6
	v_mul_f32_e32 v8, v7, v6
	v_fma_f32 v9, -v5, v8, v7
	v_fmac_f32_e32 v8, v9, v6
	v_fma_f32 v5, -v5, v8, v7
	v_div_fmas_f32 v5, v5, v6, v8
	v_div_fixup_f32 v3, v5, v4, v32
	v_bfe_u32 v4, v3, 16, 1
	v_add3_u32 v3, v3, v4, s12
	ds_write_b16_d16_hi v45, v3 offset:30464
	s_waitcnt vmcnt(10)
	v_mul_f32_e32 v4, 0xbfb8aa3b, v33
	v_exp_f32_e32 v4, v4
	s_nop 0
	v_add_f32_e32 v4, 1.0, v4
	v_div_scale_f32 v5, s[36:37], v4, v4, v33
	v_rcp_f32_e32 v6, v5
	v_div_scale_f32 v7, vcc, v33, v4, v33
	v_fma_f32 v8, -v5, v6, 1.0
	v_fmac_f32_e32 v6, v8, v6
	v_mul_f32_e32 v8, v7, v6
	v_fma_f32 v9, -v5, v8, v7
	v_fmac_f32_e32 v8, v9, v6
	v_fma_f32 v5, -v5, v8, v7
	v_div_fmas_f32 v5, v5, v6, v8
	v_div_fixup_f32 v3, v5, v4, v33
	v_bfe_u32 v4, v3, 16, 1
	v_add3_u32 v3, v3, v4, s12
	ds_write_b16_d16_hi v45, v3 offset:31008
	s_waitcnt vmcnt(9)
	v_mul_f32_e32 v4, 0xbfb8aa3b, v34
	v_exp_f32_e32 v4, v4
	s_nop 0
	v_add_f32_e32 v4, 1.0, v4
	v_div_scale_f32 v5, s[36:37], v4, v4, v34
	v_rcp_f32_e32 v6, v5
	v_div_scale_f32 v7, vcc, v34, v4, v34
	v_fma_f32 v8, -v5, v6, 1.0
	v_fmac_f32_e32 v6, v8, v6
	v_mul_f32_e32 v8, v7, v6
	v_fma_f32 v9, -v5, v8, v7
	v_fmac_f32_e32 v8, v9, v6
	v_fma_f32 v5, -v5, v8, v7
	v_div_fmas_f32 v5, v5, v6, v8
	v_div_fixup_f32 v3, v5, v4, v34
	v_bfe_u32 v4, v3, 16, 1
	v_add3_u32 v3, v3, v4, s12
	ds_write_b16_d16_hi v45, v3 offset:31552
	s_waitcnt vmcnt(8)
	v_mul_f32_e32 v4, 0xbfb8aa3b, v35
	v_exp_f32_e32 v4, v4
	s_nop 0
	v_add_f32_e32 v4, 1.0, v4
	v_div_scale_f32 v5, s[36:37], v4, v4, v35
	v_rcp_f32_e32 v6, v5
	v_div_scale_f32 v7, vcc, v35, v4, v35
	v_fma_f32 v8, -v5, v6, 1.0
	v_fmac_f32_e32 v6, v8, v6
	v_mul_f32_e32 v8, v7, v6
	v_fma_f32 v9, -v5, v8, v7
	v_fmac_f32_e32 v8, v9, v6
	v_fma_f32 v5, -v5, v8, v7
	v_div_fmas_f32 v5, v5, v6, v8
	v_div_fixup_f32 v3, v5, v4, v35
	v_bfe_u32 v4, v3, 16, 1
	v_add3_u32 v3, v3, v4, s12
	ds_write_b16_d16_hi v45, v3 offset:32096
	s_waitcnt vmcnt(7)
	v_mul_f32_e32 v4, 0xbfb8aa3b, v36
	v_exp_f32_e32 v4, v4
	s_nop 0
	v_add_f32_e32 v4, 1.0, v4
	v_div_scale_f32 v5, s[36:37], v4, v4, v36
	v_rcp_f32_e32 v6, v5
	v_div_scale_f32 v7, vcc, v36, v4, v36
	v_fma_f32 v8, -v5, v6, 1.0
	v_fmac_f32_e32 v6, v8, v6
	v_mul_f32_e32 v8, v7, v6
	v_fma_f32 v9, -v5, v8, v7
	v_fmac_f32_e32 v8, v9, v6
	v_fma_f32 v5, -v5, v8, v7
	v_div_fmas_f32 v5, v5, v6, v8
	v_div_fixup_f32 v3, v5, v4, v36
	v_bfe_u32 v4, v3, 16, 1
	v_add3_u32 v3, v3, v4, s12
	ds_write_b16_d16_hi v45, v3 offset:32640
	s_waitcnt vmcnt(6)
	v_mul_f32_e32 v4, 0xbfb8aa3b, v37
	v_exp_f32_e32 v4, v4
	s_nop 0
	v_add_f32_e32 v4, 1.0, v4
	v_div_scale_f32 v5, s[36:37], v4, v4, v37
	v_rcp_f32_e32 v6, v5
	v_div_scale_f32 v7, vcc, v37, v4, v37
	v_fma_f32 v8, -v5, v6, 1.0
	v_fmac_f32_e32 v6, v8, v6
	v_mul_f32_e32 v8, v7, v6
	v_fma_f32 v9, -v5, v8, v7
	v_fmac_f32_e32 v8, v9, v6
	v_fma_f32 v5, -v5, v8, v7
	v_div_fmas_f32 v5, v5, v6, v8
	v_div_fixup_f32 v3, v5, v4, v37
	v_bfe_u32 v4, v3, 16, 1
	v_add3_u32 v3, v3, v4, s12
	ds_write_b16_d16_hi v45, v3 offset:33184
	s_waitcnt vmcnt(5)
	v_mul_f32_e32 v4, 0xbfb8aa3b, v38
	v_exp_f32_e32 v4, v4
	s_nop 0
	v_add_f32_e32 v4, 1.0, v4
	v_div_scale_f32 v5, s[36:37], v4, v4, v38
	v_rcp_f32_e32 v6, v5
	v_div_scale_f32 v7, vcc, v38, v4, v38
	v_fma_f32 v8, -v5, v6, 1.0
	v_fmac_f32_e32 v6, v8, v6
	v_mul_f32_e32 v8, v7, v6
	v_fma_f32 v9, -v5, v8, v7
	v_fmac_f32_e32 v8, v9, v6
	v_fma_f32 v5, -v5, v8, v7
	v_div_fmas_f32 v5, v5, v6, v8
	v_div_fixup_f32 v3, v5, v4, v38
	v_bfe_u32 v4, v3, 16, 1
	v_add3_u32 v3, v3, v4, s12
	ds_write_b16_d16_hi v45, v3 offset:33728
	s_waitcnt vmcnt(4)
	v_mul_f32_e32 v4, 0xbfb8aa3b, v39
	v_exp_f32_e32 v4, v4
	s_nop 0
	v_add_f32_e32 v4, 1.0, v4
	v_div_scale_f32 v5, s[36:37], v4, v4, v39
	v_rcp_f32_e32 v6, v5
	v_div_scale_f32 v7, vcc, v39, v4, v39
	v_fma_f32 v8, -v5, v6, 1.0
	v_fmac_f32_e32 v6, v8, v6
	v_mul_f32_e32 v8, v7, v6
	v_fma_f32 v9, -v5, v8, v7
	v_fmac_f32_e32 v8, v9, v6
	v_fma_f32 v5, -v5, v8, v7
	v_div_fmas_f32 v5, v5, v6, v8
	v_div_fixup_f32 v3, v5, v4, v39
	v_bfe_u32 v4, v3, 16, 1
	v_add3_u32 v3, v3, v4, s12
	ds_write_b16_d16_hi v45, v3 offset:34272
	s_waitcnt vmcnt(3)
	v_mul_f32_e32 v4, 0xbfb8aa3b, v40
	v_exp_f32_e32 v4, v4
	s_nop 0
	v_add_f32_e32 v4, 1.0, v4
	v_div_scale_f32 v5, s[36:37], v4, v4, v40
	v_rcp_f32_e32 v6, v5
	v_div_scale_f32 v7, vcc, v40, v4, v40
	v_fma_f32 v8, -v5, v6, 1.0
	v_fmac_f32_e32 v6, v8, v6
	v_mul_f32_e32 v8, v7, v6
	v_fma_f32 v9, -v5, v8, v7
	v_fmac_f32_e32 v8, v9, v6
	v_fma_f32 v5, -v5, v8, v7
	v_div_fmas_f32 v5, v5, v6, v8
	v_div_fixup_f32 v3, v5, v4, v40
	v_bfe_u32 v4, v3, 16, 1
	v_add3_u32 v3, v3, v4, s12
	ds_write_b16_d16_hi v45, v3 offset:34816
	s_waitcnt vmcnt(2)
	v_mul_f32_e32 v4, 0xbfb8aa3b, v41
	v_exp_f32_e32 v4, v4
	s_nop 0
	v_add_f32_e32 v4, 1.0, v4
	v_div_scale_f32 v5, s[36:37], v4, v4, v41
	v_rcp_f32_e32 v6, v5
	v_div_scale_f32 v7, vcc, v41, v4, v41
	v_fma_f32 v8, -v5, v6, 1.0
	v_fmac_f32_e32 v6, v8, v6
	v_mul_f32_e32 v8, v7, v6
	v_fma_f32 v9, -v5, v8, v7
	v_fmac_f32_e32 v8, v9, v6
	v_fma_f32 v5, -v5, v8, v7
	v_div_fmas_f32 v5, v5, v6, v8
	v_div_fixup_f32 v3, v5, v4, v41
	v_bfe_u32 v4, v3, 16, 1
	v_add3_u32 v3, v3, v4, s12
	ds_write_b16_d16_hi v45, v3 offset:35360
	s_waitcnt vmcnt(1)
	v_mul_f32_e32 v4, 0xbfb8aa3b, v42
	v_exp_f32_e32 v4, v4
	s_nop 0
	v_add_f32_e32 v4, 1.0, v4
	v_div_scale_f32 v5, s[36:37], v4, v4, v42
	v_rcp_f32_e32 v6, v5
	v_div_scale_f32 v7, vcc, v42, v4, v42
	v_fma_f32 v8, -v5, v6, 1.0
	v_fmac_f32_e32 v6, v8, v6
	v_mul_f32_e32 v8, v7, v6
	v_fma_f32 v9, -v5, v8, v7
	v_fmac_f32_e32 v8, v9, v6
	v_fma_f32 v5, -v5, v8, v7
	v_div_fmas_f32 v5, v5, v6, v8
	v_div_fixup_f32 v3, v5, v4, v42
	v_bfe_u32 v4, v3, 16, 1
	v_add3_u32 v3, v3, v4, s12
	ds_write_b16_d16_hi v45, v3 offset:35904
	s_waitcnt vmcnt(0)
	v_mul_f32_e32 v4, 0xbfb8aa3b, v43
	v_exp_f32_e32 v4, v4
	s_nop 0
	v_add_f32_e32 v4, 1.0, v4
	v_div_scale_f32 v5, s[36:37], v4, v4, v43
	v_rcp_f32_e32 v6, v5
	v_div_scale_f32 v7, vcc, v43, v4, v43
	v_fma_f32 v8, -v5, v6, 1.0
	v_fmac_f32_e32 v6, v8, v6
	v_mul_f32_e32 v8, v7, v6
	v_fma_f32 v9, -v5, v8, v7
	v_fmac_f32_e32 v8, v9, v6
	v_fma_f32 v5, -v5, v8, v7
	v_div_fmas_f32 v5, v5, v6, v8
	v_div_fixup_f32 v3, v5, v4, v43
	v_bfe_u32 v4, v3, 16, 1
	v_add3_u32 v3, v3, v4, s12
	ds_write_b16_d16_hi v45, v3 offset:36448
	v_mov_b32_e32 v46, 0
	ds_write_b16 v45, v46 offset:36992
	ds_write_b16 v45, v46 offset:37536
	ds_write_b16 v45, v46 offset:38080
	ds_write_b16 v45, v46 offset:38624
	ds_write_b16 v45, v46 offset:39168
	ds_write_b16 v45, v46 offset:39712
	ds_write_b16 v45, v46 offset:40256
	ds_write_b16 v45, v46 offset:40800
	ds_write_b16 v45, v46 offset:41344
	ds_write_b16 v45, v46 offset:41888
	ds_write_b16 v45, v46 offset:42432
	ds_write_b16 v45, v46 offset:42976
